# P2 branch-gates epilogue: bias add and -log2e scale folded into one fmamk, computed in place (asm guide 7.5 instruction selection)
# speedup vs baseline: 1.0065x; 1.0050x over previous
; __device__ __forceinline__ u32x4 pack8(const float (&v)[8]) { u32x4 w; w.x = cvtpk(v[0], v[1]); w.y = cvtpk(v[2], v[3]); w.z = cvtpk(v[4], v[5]); w.w = cvtpk(v[6], v[7]); return w; }
;     __device__ __forceinline__ void operator()(const pg8::f32x4 (&acc)[2][2][4][2], const pg8::Unit& u, int wr, int wc, int fr, int fq) const {
;     ...
;                 const int c0 = (u.pn - 8) * 128 + wc * 32 + 8 * fq; float ba[8], bp[8];
; #pragma unroll
;                 for (int h = 0; h < 2; ++h) { const f32x4 a = *(const f32x4*)(rest.gate_b + c0 + 4 * h), p = *(const f32x4*)(rest.gate_b + 1024 + c0 + 4 * h);
; #pragma unroll
;                     for (int i = 0; i < 4; ++i) { ba[4 * h + i] = a[i]; bp[4 * h + i] = p[i]; } }
; #pragma unroll
;                 for (int ai = 0; ai < 2; ++ai)
; #pragma unroll
;                     for (int m = 0; m < 4; ++m) { ACC8(va, ai, 0, m); ACC8(vp, ai, 1, m); float oa[8], orr[8];
; #pragma unroll
;                         for (int i = 0; i < 8; ++i) { const float ea = fminf(1.0f + __builtin_amdgcn_exp2f(-LOG2E * (va[i] + ba[i])), 1e30f), ep = 1.0f + __builtin_amdgcn_exp2f(-LOG2E * (vp[i] + bp[i]));
;                             oa[i] = __builtin_amdgcn_rcpf(ea); orr[i] = ea * __builtin_amdgcn_rcpf(ep); }
;                         bf16_t* gp_ = rest.GATES + (size_t)(u.pm * 256 + ai * 128 + wr * 64 + m * 16 + fr) * 2048 + c0;
;                         *(u32x4*)gp_ = pack8(oa); *(u32x4*)(gp_ + 1024) = pack8(orr); }
.LBB9_238:
	s_cmp_lg_u32 s33, 5
	s_cbranch_scc0 .LBB9_244
	s_cmp_gt_u32 s33, 7
	s_cbranch_scc0 .LBB9_241
	v_lshl_add_u32 v146, s33, 7, v183
	v_mov_b32_e32 v147, v161
	v_readlane_b32 s64, v251, 16
	v_lshlrev_b64 v[128:129], 2, v[146:147]
	v_readlane_b32 s66, v251, 18
	v_readlane_b32 s67, v251, 19
	s_lshl_b32 s2, s30, 8
	v_lshlrev_b64 v[146:147], 1, v[146:147]
	v_lshl_add_u64 v[130:131], s[66:67], 0, v[128:129]
	v_lshl_add_u64 v[128:129], s[20:21], 0, v[128:129]
	global_load_dwordx4 v[140:143], v[130:131], off
	global_load_dwordx4 v[136:139], v[128:129], off
	global_load_dwordx4 v[132:135], v[130:131], off offset:16
	s_nop 0
	global_load_dwordx4 v[128:131], v[128:129], off offset:16
	v_readlane_b32 s65, v251, 17
	v_readlane_b32 s68, v251, 20
	v_readlane_b32 s69, v251, 21
	v_readlane_b32 s70, v251, 22
	v_readlane_b32 s71, v251, 23
	v_readlane_b32 s72, v251, 24
	v_readlane_b32 s73, v251, 25
	v_readlane_b32 s74, v251, 26
	v_readlane_b32 s75, v251, 27
	v_readlane_b32 s76, v251, 28
	v_readlane_b32 s77, v251, 29
	v_readlane_b32 s78, v251, 30
	v_readlane_b32 s79, v251, 31
	s_waitcnt vmcnt(0)
	v_mul_f32_e32 v140, 0xbfb8aa3b, v140
	v_mul_f32_e32 v141, 0xbfb8aa3b, v141
	v_mul_f32_e32 v142, 0xbfb8aa3b, v142
	v_mul_f32_e32 v143, 0xbfb8aa3b, v143
	v_mul_f32_e32 v132, 0xbfb8aa3b, v132
	v_mul_f32_e32 v133, 0xbfb8aa3b, v133
	v_mul_f32_e32 v134, 0xbfb8aa3b, v134
	v_mul_f32_e32 v135, 0xbfb8aa3b, v135
	v_mul_f32_e32 v136, 0xbfb8aa3b, v136
	v_mul_f32_e32 v137, 0xbfb8aa3b, v137
	v_mul_f32_e32 v138, 0xbfb8aa3b, v138
	v_mul_f32_e32 v139, 0xbfb8aa3b, v139
	v_mul_f32_e32 v128, 0xbfb8aa3b, v128
	v_mul_f32_e32 v129, 0xbfb8aa3b, v129
	v_mul_f32_e32 v130, 0xbfb8aa3b, v130
	v_mul_f32_e32 v131, 0xbfb8aa3b, v131
	v_add_u32_e32 v144, s2, v180
	v_fmamk_f32 v124, v124, 0xbfb8aa3b, v140
	v_fmamk_f32 v125, v125, 0xbfb8aa3b, v141
	v_fmamk_f32 v126, v126, 0xbfb8aa3b, v142
	v_fmamk_f32 v127, v127, 0xbfb8aa3b, v143
	v_fmamk_f32 v120, v120, 0xbfb8aa3b, v132
	v_fmamk_f32 v121, v121, 0xbfb8aa3b, v133
	v_fmamk_f32 v122, v122, 0xbfb8aa3b, v134
	v_fmamk_f32 v123, v123, 0xbfb8aa3b, v135
	v_fmamk_f32 v116, v116, 0xbfb8aa3b, v136
	v_fmamk_f32 v117, v117, 0xbfb8aa3b, v137
	v_fmamk_f32 v118, v118, 0xbfb8aa3b, v138
	v_fmamk_f32 v119, v119, 0xbfb8aa3b, v139
	v_fmamk_f32 v112, v112, 0xbfb8aa3b, v128
	v_fmamk_f32 v113, v113, 0xbfb8aa3b, v129
	v_fmamk_f32 v114, v114, 0xbfb8aa3b, v130
	v_fmamk_f32 v115, v115, 0xbfb8aa3b, v131
	v_exp_f32_e32 v124, v124
	v_exp_f32_e32 v125, v125
	v_exp_f32_e32 v126, v126
	v_exp_f32_e32 v127, v127
	v_exp_f32_e32 v120, v120
	v_exp_f32_e32 v121, v121
	v_exp_f32_e32 v122, v122
	v_exp_f32_e32 v123, v123
	v_exp_f32_e32 v116, v116
	v_exp_f32_e32 v117, v117
	v_exp_f32_e32 v118, v118
	v_exp_f32_e32 v119, v119
	v_exp_f32_e32 v112, v112
	v_exp_f32_e32 v113, v113
	v_exp_f32_e32 v114, v114
	v_exp_f32_e32 v115, v115
	v_add_f32_e32 v124, 1.0, v124
	v_add_f32_e32 v125, 1.0, v125
	v_add_f32_e32 v126, 1.0, v126
	v_add_f32_e32 v127, 1.0, v127
	v_add_f32_e32 v120, 1.0, v120
	v_add_f32_e32 v121, 1.0, v121
	v_add_f32_e32 v122, 1.0, v122
	v_add_f32_e32 v123, 1.0, v123
	v_add_f32_e32 v116, 1.0, v116
	v_add_f32_e32 v117, 1.0, v117
	v_add_f32_e32 v118, 1.0, v118
	v_add_f32_e32 v119, 1.0, v119
	v_add_f32_e32 v112, 1.0, v112
	v_add_f32_e32 v113, 1.0, v113
	v_add_f32_e32 v114, 1.0, v114
	v_add_f32_e32 v115, 1.0, v115
	v_min_f32_e32 v124, 0x7149f2ca, v124
	v_min_f32_e32 v125, 0x7149f2ca, v125
	v_min_f32_e32 v126, 0x7149f2ca, v126
	v_min_f32_e32 v127, 0x7149f2ca, v127
	v_min_f32_e32 v120, 0x7149f2ca, v120
	v_min_f32_e32 v121, 0x7149f2ca, v121
	v_min_f32_e32 v122, 0x7149f2ca, v122
	v_min_f32_e32 v123, 0x7149f2ca, v123
	v_rcp_f32_e32 v116, v116
	v_rcp_f32_e32 v117, v117
	v_rcp_f32_e32 v118, v118
	v_rcp_f32_e32 v119, v119
	v_rcp_f32_e32 v112, v112
	v_rcp_f32_e32 v113, v113
	v_rcp_f32_e32 v114, v114
	v_rcp_f32_e32 v115, v115
	v_mov_b32_e32 v204, v144
	v_ashrrev_i32_e32 v205, 31, v204
	v_lshlrev_b64 v[204:205], 12, v[204:205]
	v_lshl_add_u64 v[204:205], s[12:13], 0, v[204:205]
	v_lshl_add_u64 v[204:205], v[204:205], 0, v[146:147]
	v_mul_f32_e32 v116, v124, v116
	v_mul_f32_e32 v117, v125, v117
	v_mul_f32_e32 v118, v126, v118
	v_mul_f32_e32 v119, v127, v119
	v_mul_f32_e32 v112, v120, v112
	v_mul_f32_e32 v113, v121, v113
	v_mul_f32_e32 v114, v122, v114
	v_mul_f32_e32 v115, v123, v115
	v_rcp_f32_e32 v124, v124
	v_rcp_f32_e32 v125, v125
	v_rcp_f32_e32 v126, v126
	v_rcp_f32_e32 v127, v127
	v_rcp_f32_e32 v120, v120
	v_rcp_f32_e32 v121, v121
	v_rcp_f32_e32 v122, v122
	v_rcp_f32_e32 v123, v123
	v_cvt_pk_bf16_f32 v176, v116, v117
	v_cvt_pk_bf16_f32 v177, v118, v119
	v_cvt_pk_bf16_f32 v178, v112, v113
	v_cvt_pk_bf16_f32 v179, v114, v115
	v_cvt_pk_bf16_f32 v148, v124, v125
	v_cvt_pk_bf16_f32 v149, v126, v127
	v_cvt_pk_bf16_f32 v150, v120, v121
	v_cvt_pk_bf16_f32 v151, v122, v123
	global_store_dwordx4 v[204:205], v[148:151], off
	global_store_dwordx4 v[204:205], v[176:179], off offset:2048
	v_fmamk_f32 v108, v108, 0xbfb8aa3b, v140
	v_fmamk_f32 v109, v109, 0xbfb8aa3b, v141
	v_fmamk_f32 v110, v110, 0xbfb8aa3b, v142
	v_fmamk_f32 v111, v111, 0xbfb8aa3b, v143
	v_fmamk_f32 v104, v104, 0xbfb8aa3b, v132
	v_fmamk_f32 v105, v105, 0xbfb8aa3b, v133
	v_fmamk_f32 v106, v106, 0xbfb8aa3b, v134
	v_fmamk_f32 v107, v107, 0xbfb8aa3b, v135
	v_fmamk_f32 v100, v100, 0xbfb8aa3b, v136
	v_fmamk_f32 v101, v101, 0xbfb8aa3b, v137
	v_fmamk_f32 v102, v102, 0xbfb8aa3b, v138
	v_fmamk_f32 v103, v103, 0xbfb8aa3b, v139
	v_fmamk_f32 v96, v96, 0xbfb8aa3b, v128
	v_fmamk_f32 v97, v97, 0xbfb8aa3b, v129
	v_fmamk_f32 v98, v98, 0xbfb8aa3b, v130
	v_fmamk_f32 v99, v99, 0xbfb8aa3b, v131
	v_exp_f32_e32 v108, v108
	v_exp_f32_e32 v109, v109
	v_exp_f32_e32 v110, v110
; __device__ __forceinline__ u32x4 pack8(const float (&v)[8]) { u32x4 w; w.x = cvtpk(v[0], v[1]); w.y = cvtpk(v[2], v[3]); w.z = cvtpk(v[4], v[5]); w.w = cvtpk(v[6], v[7]); return w; }
;     __device__ __forceinline__ void operator()(const pg8::f32x4 (&acc)[2][2][4][2], const pg8::Unit& u, int wr, int wc, int fr, int fq) const {
;     ...
;                 const int c0 = (u.pn - 8) * 128 + wc * 32 + 8 * fq; float ba[8], bp[8];
; #pragma unroll
;                 for (int h = 0; h < 2; ++h) { const f32x4 a = *(const f32x4*)(rest.gate_b + c0 + 4 * h), p = *(const f32x4*)(rest.gate_b + 1024 + c0 + 4 * h);
; #pragma unroll
;                     for (int i = 0; i < 4; ++i) { ba[4 * h + i] = a[i]; bp[4 * h + i] = p[i]; } }
; #pragma unroll
;                 for (int ai = 0; ai < 2; ++ai)
; #pragma unroll
;                     for (int m = 0; m < 4; ++m) { ACC8(va, ai, 0, m); ACC8(vp, ai, 1, m); float oa[8], orr[8];
; #pragma unroll
;                         for (int i = 0; i < 8; ++i) { const float ea = fminf(1.0f + __builtin_amdgcn_exp2f(-LOG2E * (va[i] + ba[i])), 1e30f), ep = 1.0f + __builtin_amdgcn_exp2f(-LOG2E * (vp[i] + bp[i]));
;                             oa[i] = __builtin_amdgcn_rcpf(ea); orr[i] = ea * __builtin_amdgcn_rcpf(ep); }
;                         bf16_t* gp_ = rest.GATES + (size_t)(u.pm * 256 + ai * 128 + wr * 64 + m * 16 + fr) * 2048 + c0;
;                         *(u32x4*)gp_ = pack8(oa); *(u32x4*)(gp_ + 1024) = pack8(orr); }
	v_exp_f32_e32 v111, v111
	v_exp_f32_e32 v104, v104
	v_exp_f32_e32 v105, v105
	v_exp_f32_e32 v106, v106
	v_exp_f32_e32 v107, v107
	v_exp_f32_e32 v100, v100
	v_exp_f32_e32 v101, v101
	v_exp_f32_e32 v102, v102
	v_exp_f32_e32 v103, v103
	v_exp_f32_e32 v96, v96
	v_exp_f32_e32 v97, v97
	v_exp_f32_e32 v98, v98
	v_exp_f32_e32 v99, v99
	v_add_f32_e32 v108, 1.0, v108
	v_add_f32_e32 v109, 1.0, v109
	v_add_f32_e32 v110, 1.0, v110
	v_add_f32_e32 v111, 1.0, v111
	v_add_f32_e32 v104, 1.0, v104
	v_add_f32_e32 v105, 1.0, v105
	v_add_f32_e32 v106, 1.0, v106
	v_add_f32_e32 v107, 1.0, v107
	v_add_f32_e32 v100, 1.0, v100
	v_add_f32_e32 v101, 1.0, v101
	v_add_f32_e32 v102, 1.0, v102
	v_add_f32_e32 v103, 1.0, v103
	v_add_f32_e32 v96, 1.0, v96
	v_add_f32_e32 v97, 1.0, v97
	v_add_f32_e32 v98, 1.0, v98
	v_add_f32_e32 v99, 1.0, v99
	v_min_f32_e32 v108, 0x7149f2ca, v108
	v_min_f32_e32 v109, 0x7149f2ca, v109
	v_min_f32_e32 v110, 0x7149f2ca, v110
	v_min_f32_e32 v111, 0x7149f2ca, v111
	v_min_f32_e32 v104, 0x7149f2ca, v104
	v_min_f32_e32 v105, 0x7149f2ca, v105
	v_min_f32_e32 v106, 0x7149f2ca, v106
	v_min_f32_e32 v107, 0x7149f2ca, v107
	v_rcp_f32_e32 v100, v100
	v_rcp_f32_e32 v101, v101
	v_rcp_f32_e32 v102, v102
	v_rcp_f32_e32 v103, v103
	v_rcp_f32_e32 v96, v96
	v_rcp_f32_e32 v97, v97
	v_rcp_f32_e32 v98, v98
	v_rcp_f32_e32 v99, v99
	v_add_u32_e32 v206, 0x10, v144
	v_ashrrev_i32_e32 v207, 31, v206
	v_lshlrev_b64 v[206:207], 12, v[206:207]
	v_lshl_add_u64 v[206:207], s[12:13], 0, v[206:207]
	v_lshl_add_u64 v[206:207], v[206:207], 0, v[146:147]
	v_mul_f32_e32 v100, v108, v100
	v_mul_f32_e32 v101, v109, v101
	v_mul_f32_e32 v102, v110, v102
	v_mul_f32_e32 v103, v111, v103
	v_mul_f32_e32 v96, v104, v96
	v_mul_f32_e32 v97, v105, v97
	v_mul_f32_e32 v98, v106, v98
	v_mul_f32_e32 v99, v107, v99
	v_rcp_f32_e32 v108, v108
	v_rcp_f32_e32 v109, v109
	v_rcp_f32_e32 v110, v110
	v_rcp_f32_e32 v111, v111
	v_rcp_f32_e32 v104, v104
	v_rcp_f32_e32 v105, v105
	v_rcp_f32_e32 v106, v106
	v_rcp_f32_e32 v107, v107
	v_cvt_pk_bf16_f32 v176, v100, v101
	v_cvt_pk_bf16_f32 v177, v102, v103
	v_cvt_pk_bf16_f32 v178, v96, v97
	v_cvt_pk_bf16_f32 v179, v98, v99
	v_cvt_pk_bf16_f32 v148, v108, v109
	v_cvt_pk_bf16_f32 v149, v110, v111
	v_cvt_pk_bf16_f32 v150, v104, v105
	v_cvt_pk_bf16_f32 v151, v106, v107
	global_store_dwordx4 v[206:207], v[148:151], off
	global_store_dwordx4 v[206:207], v[176:179], off offset:2048
	v_fmamk_f32 v92, v92, 0xbfb8aa3b, v140
	v_fmamk_f32 v93, v93, 0xbfb8aa3b, v141
	v_fmamk_f32 v94, v94, 0xbfb8aa3b, v142
	v_fmamk_f32 v95, v95, 0xbfb8aa3b, v143
	v_fmamk_f32 v88, v88, 0xbfb8aa3b, v132
	v_fmamk_f32 v89, v89, 0xbfb8aa3b, v133
	v_fmamk_f32 v90, v90, 0xbfb8aa3b, v134
	v_fmamk_f32 v91, v91, 0xbfb8aa3b, v135
	v_fmamk_f32 v84, v84, 0xbfb8aa3b, v136
	v_fmamk_f32 v85, v85, 0xbfb8aa3b, v137
	v_fmamk_f32 v86, v86, 0xbfb8aa3b, v138
	v_fmamk_f32 v87, v87, 0xbfb8aa3b, v139
	v_fmamk_f32 v80, v80, 0xbfb8aa3b, v128
	v_fmamk_f32 v81, v81, 0xbfb8aa3b, v129
	v_fmamk_f32 v82, v82, 0xbfb8aa3b, v130
	v_fmamk_f32 v83, v83, 0xbfb8aa3b, v131
	v_exp_f32_e32 v92, v92
	v_exp_f32_e32 v93, v93
	v_exp_f32_e32 v94, v94
	v_exp_f32_e32 v95, v95
	v_exp_f32_e32 v88, v88
	v_exp_f32_e32 v89, v89
	v_exp_f32_e32 v90, v90
	v_exp_f32_e32 v91, v91
	v_exp_f32_e32 v84, v84
	v_exp_f32_e32 v85, v85
	v_exp_f32_e32 v86, v86
	v_exp_f32_e32 v87, v87
	v_exp_f32_e32 v80, v80
	v_exp_f32_e32 v81, v81
	v_exp_f32_e32 v82, v82
	v_exp_f32_e32 v83, v83
	v_add_f32_e32 v92, 1.0, v92
	v_add_f32_e32 v93, 1.0, v93
	v_add_f32_e32 v94, 1.0, v94
	v_add_f32_e32 v95, 1.0, v95
	v_add_f32_e32 v88, 1.0, v88
	v_add_f32_e32 v89, 1.0, v89
	v_add_f32_e32 v90, 1.0, v90
	v_add_f32_e32 v91, 1.0, v91
	v_add_f32_e32 v84, 1.0, v84
	v_add_f32_e32 v85, 1.0, v85
	v_add_f32_e32 v86, 1.0, v86
	v_add_f32_e32 v87, 1.0, v87
	v_add_f32_e32 v80, 1.0, v80
	v_add_f32_e32 v81, 1.0, v81
	v_add_f32_e32 v82, 1.0, v82
	v_add_f32_e32 v83, 1.0, v83
	v_min_f32_e32 v92, 0x7149f2ca, v92
	v_min_f32_e32 v93, 0x7149f2ca, v93
	v_min_f32_e32 v94, 0x7149f2ca, v94
	v_min_f32_e32 v95, 0x7149f2ca, v95
	v_min_f32_e32 v88, 0x7149f2ca, v88
	v_min_f32_e32 v89, 0x7149f2ca, v89
	v_min_f32_e32 v90, 0x7149f2ca, v90
	v_min_f32_e32 v91, 0x7149f2ca, v91
	v_rcp_f32_e32 v84, v84
	v_rcp_f32_e32 v85, v85
	v_rcp_f32_e32 v86, v86
	v_rcp_f32_e32 v87, v87
	v_rcp_f32_e32 v80, v80
	v_rcp_f32_e32 v81, v81
	v_rcp_f32_e32 v82, v82
	v_rcp_f32_e32 v83, v83
	v_add_u32_e32 v204, 0x20, v144
	v_ashrrev_i32_e32 v205, 31, v204
	v_lshlrev_b64 v[204:205], 12, v[204:205]
	v_lshl_add_u64 v[204:205], s[12:13], 0, v[204:205]
	v_lshl_add_u64 v[204:205], v[204:205], 0, v[146:147]
	v_mul_f32_e32 v84, v92, v84
	v_mul_f32_e32 v85, v93, v85
	v_mul_f32_e32 v86, v94, v86
	v_mul_f32_e32 v87, v95, v87
	v_mul_f32_e32 v80, v88, v80
	v_mul_f32_e32 v81, v89, v81
	v_mul_f32_e32 v82, v90, v82
	v_mul_f32_e32 v83, v91, v83
	v_rcp_f32_e32 v92, v92
	v_rcp_f32_e32 v93, v93
	v_rcp_f32_e32 v94, v94
	v_rcp_f32_e32 v95, v95
	v_rcp_f32_e32 v88, v88
	v_rcp_f32_e32 v89, v89
	v_rcp_f32_e32 v90, v90
	v_rcp_f32_e32 v91, v91
	v_cvt_pk_bf16_f32 v176, v84, v85
	v_cvt_pk_bf16_f32 v177, v86, v87
	v_cvt_pk_bf16_f32 v178, v80, v81
	v_cvt_pk_bf16_f32 v179, v82, v83
	v_cvt_pk_bf16_f32 v148, v92, v93
	v_cvt_pk_bf16_f32 v149, v94, v95
	v_cvt_pk_bf16_f32 v150, v88, v89
	v_cvt_pk_bf16_f32 v151, v90, v91
	global_store_dwordx4 v[204:205], v[148:151], off
	global_store_dwordx4 v[204:205], v[176:179], off offset:2048
	v_fmamk_f32 v76, v76, 0xbfb8aa3b, v140
	v_fmamk_f32 v77, v77, 0xbfb8aa3b, v141
	v_fmamk_f32 v78, v78, 0xbfb8aa3b, v142
	v_fmamk_f32 v79, v79, 0xbfb8aa3b, v143
	v_fmamk_f32 v72, v72, 0xbfb8aa3b, v132
	v_fmamk_f32 v73, v73, 0xbfb8aa3b, v133
	v_fmamk_f32 v74, v74, 0xbfb8aa3b, v134
; __device__ __forceinline__ u32x4 pack8(const float (&v)[8]) { u32x4 w; w.x = cvtpk(v[0], v[1]); w.y = cvtpk(v[2], v[3]); w.z = cvtpk(v[4], v[5]); w.w = cvtpk(v[6], v[7]); return w; }
;     __device__ __forceinline__ void operator()(const pg8::f32x4 (&acc)[2][2][4][2], const pg8::Unit& u, int wr, int wc, int fr, int fq) const {
;     ...
;                 const int c0 = (u.pn - 8) * 128 + wc * 32 + 8 * fq; float ba[8], bp[8];
; #pragma unroll
;                 for (int h = 0; h < 2; ++h) { const f32x4 a = *(const f32x4*)(rest.gate_b + c0 + 4 * h), p = *(const f32x4*)(rest.gate_b + 1024 + c0 + 4 * h);
; #pragma unroll
;                     for (int i = 0; i < 4; ++i) { ba[4 * h + i] = a[i]; bp[4 * h + i] = p[i]; } }
; #pragma unroll
;                 for (int ai = 0; ai < 2; ++ai)
; #pragma unroll
;                     for (int m = 0; m < 4; ++m) { ACC8(va, ai, 0, m); ACC8(vp, ai, 1, m); float oa[8], orr[8];
; #pragma unroll
;                         for (int i = 0; i < 8; ++i) { const float ea = fminf(1.0f + __builtin_amdgcn_exp2f(-LOG2E * (va[i] + ba[i])), 1e30f), ep = 1.0f + __builtin_amdgcn_exp2f(-LOG2E * (vp[i] + bp[i]));
;                             oa[i] = __builtin_amdgcn_rcpf(ea); orr[i] = ea * __builtin_amdgcn_rcpf(ep); }
;                         bf16_t* gp_ = rest.GATES + (size_t)(u.pm * 256 + ai * 128 + wr * 64 + m * 16 + fr) * 2048 + c0;
;                         *(u32x4*)gp_ = pack8(oa); *(u32x4*)(gp_ + 1024) = pack8(orr); }
	v_fmamk_f32 v75, v75, 0xbfb8aa3b, v135
	v_fmamk_f32 v68, v68, 0xbfb8aa3b, v136
	v_fmamk_f32 v69, v69, 0xbfb8aa3b, v137
	v_fmamk_f32 v70, v70, 0xbfb8aa3b, v138
	v_fmamk_f32 v71, v71, 0xbfb8aa3b, v139
	v_fmamk_f32 v64, v64, 0xbfb8aa3b, v128
	v_fmamk_f32 v65, v65, 0xbfb8aa3b, v129
	v_fmamk_f32 v66, v66, 0xbfb8aa3b, v130
	v_fmamk_f32 v67, v67, 0xbfb8aa3b, v131
	v_exp_f32_e32 v76, v76
	v_exp_f32_e32 v77, v77
	v_exp_f32_e32 v78, v78
	v_exp_f32_e32 v79, v79
	v_exp_f32_e32 v72, v72
	v_exp_f32_e32 v73, v73
	v_exp_f32_e32 v74, v74
	v_exp_f32_e32 v75, v75
	v_exp_f32_e32 v68, v68
	v_exp_f32_e32 v69, v69
	v_exp_f32_e32 v70, v70
	v_exp_f32_e32 v71, v71
	v_exp_f32_e32 v64, v64
	v_exp_f32_e32 v65, v65
	v_exp_f32_e32 v66, v66
	v_exp_f32_e32 v67, v67
	v_add_f32_e32 v76, 1.0, v76
	v_add_f32_e32 v77, 1.0, v77
	v_add_f32_e32 v78, 1.0, v78
	v_add_f32_e32 v79, 1.0, v79
	v_add_f32_e32 v72, 1.0, v72
	v_add_f32_e32 v73, 1.0, v73
	v_add_f32_e32 v74, 1.0, v74
	v_add_f32_e32 v75, 1.0, v75
	v_add_f32_e32 v68, 1.0, v68
	v_add_f32_e32 v69, 1.0, v69
	v_add_f32_e32 v70, 1.0, v70
	v_add_f32_e32 v71, 1.0, v71
	v_add_f32_e32 v64, 1.0, v64
	v_add_f32_e32 v65, 1.0, v65
	v_add_f32_e32 v66, 1.0, v66
	v_add_f32_e32 v67, 1.0, v67
	v_min_f32_e32 v76, 0x7149f2ca, v76
	v_min_f32_e32 v77, 0x7149f2ca, v77
	v_min_f32_e32 v78, 0x7149f2ca, v78
	v_min_f32_e32 v79, 0x7149f2ca, v79
	v_min_f32_e32 v72, 0x7149f2ca, v72
	v_min_f32_e32 v73, 0x7149f2ca, v73
	v_min_f32_e32 v74, 0x7149f2ca, v74
	v_min_f32_e32 v75, 0x7149f2ca, v75
	v_rcp_f32_e32 v68, v68
	v_rcp_f32_e32 v69, v69
	v_rcp_f32_e32 v70, v70
	v_rcp_f32_e32 v71, v71
	v_rcp_f32_e32 v64, v64
	v_rcp_f32_e32 v65, v65
	v_rcp_f32_e32 v66, v66
	v_rcp_f32_e32 v67, v67
	v_add_u32_e32 v206, 0x30, v144
	v_ashrrev_i32_e32 v207, 31, v206
	v_lshlrev_b64 v[206:207], 12, v[206:207]
	v_lshl_add_u64 v[206:207], s[12:13], 0, v[206:207]
	v_lshl_add_u64 v[206:207], v[206:207], 0, v[146:147]
	v_mul_f32_e32 v68, v76, v68
	v_mul_f32_e32 v69, v77, v69
	v_mul_f32_e32 v70, v78, v70
	v_mul_f32_e32 v71, v79, v71
	v_mul_f32_e32 v64, v72, v64
	v_mul_f32_e32 v65, v73, v65
	v_mul_f32_e32 v66, v74, v66
	v_mul_f32_e32 v67, v75, v67
	v_rcp_f32_e32 v76, v76
	v_rcp_f32_e32 v77, v77
	v_rcp_f32_e32 v78, v78
	v_rcp_f32_e32 v79, v79
	v_rcp_f32_e32 v72, v72
	v_rcp_f32_e32 v73, v73
	v_rcp_f32_e32 v74, v74
	v_rcp_f32_e32 v75, v75
	v_cvt_pk_bf16_f32 v176, v68, v69
	v_cvt_pk_bf16_f32 v177, v70, v71
	v_cvt_pk_bf16_f32 v178, v64, v65
	v_cvt_pk_bf16_f32 v179, v66, v67
	v_cvt_pk_bf16_f32 v148, v76, v77
	v_cvt_pk_bf16_f32 v149, v78, v79
	v_cvt_pk_bf16_f32 v150, v72, v73
	v_cvt_pk_bf16_f32 v151, v74, v75
	global_store_dwordx4 v[206:207], v[148:151], off
	global_store_dwordx4 v[206:207], v[176:179], off offset:2048
	v_fmamk_f32 v60, v60, 0xbfb8aa3b, v140
	v_fmamk_f32 v61, v61, 0xbfb8aa3b, v141
	v_fmamk_f32 v62, v62, 0xbfb8aa3b, v142
	v_fmamk_f32 v63, v63, 0xbfb8aa3b, v143
	v_fmamk_f32 v56, v56, 0xbfb8aa3b, v132
	v_fmamk_f32 v57, v57, 0xbfb8aa3b, v133
	v_fmamk_f32 v58, v58, 0xbfb8aa3b, v134
	v_fmamk_f32 v59, v59, 0xbfb8aa3b, v135
	v_fmamk_f32 v52, v52, 0xbfb8aa3b, v136
	v_fmamk_f32 v53, v53, 0xbfb8aa3b, v137
	v_fmamk_f32 v54, v54, 0xbfb8aa3b, v138
	v_fmamk_f32 v55, v55, 0xbfb8aa3b, v139
	v_fmamk_f32 v48, v48, 0xbfb8aa3b, v128
	v_fmamk_f32 v49, v49, 0xbfb8aa3b, v129
	v_fmamk_f32 v50, v50, 0xbfb8aa3b, v130
	v_fmamk_f32 v51, v51, 0xbfb8aa3b, v131
	v_exp_f32_e32 v60, v60
	v_exp_f32_e32 v61, v61
	v_exp_f32_e32 v62, v62
	v_exp_f32_e32 v63, v63
	v_exp_f32_e32 v56, v56
	v_exp_f32_e32 v57, v57
	v_exp_f32_e32 v58, v58
	v_exp_f32_e32 v59, v59
	v_exp_f32_e32 v52, v52
	v_exp_f32_e32 v53, v53
	v_exp_f32_e32 v54, v54
	v_exp_f32_e32 v55, v55
	v_exp_f32_e32 v48, v48
	v_exp_f32_e32 v49, v49
	v_exp_f32_e32 v50, v50
	v_exp_f32_e32 v51, v51
	v_add_f32_e32 v60, 1.0, v60
	v_add_f32_e32 v61, 1.0, v61
	v_add_f32_e32 v62, 1.0, v62
	v_add_f32_e32 v63, 1.0, v63
	v_add_f32_e32 v56, 1.0, v56
	v_add_f32_e32 v57, 1.0, v57
	v_add_f32_e32 v58, 1.0, v58
	v_add_f32_e32 v59, 1.0, v59
	v_add_f32_e32 v52, 1.0, v52
	v_add_f32_e32 v53, 1.0, v53
	v_add_f32_e32 v54, 1.0, v54
	v_add_f32_e32 v55, 1.0, v55
	v_add_f32_e32 v48, 1.0, v48
	v_add_f32_e32 v49, 1.0, v49
	v_add_f32_e32 v50, 1.0, v50
	v_add_f32_e32 v51, 1.0, v51
	v_min_f32_e32 v60, 0x7149f2ca, v60
	v_min_f32_e32 v61, 0x7149f2ca, v61
	v_min_f32_e32 v62, 0x7149f2ca, v62
	v_min_f32_e32 v63, 0x7149f2ca, v63
	v_min_f32_e32 v56, 0x7149f2ca, v56
	v_min_f32_e32 v57, 0x7149f2ca, v57
	v_min_f32_e32 v58, 0x7149f2ca, v58
	v_min_f32_e32 v59, 0x7149f2ca, v59
	v_rcp_f32_e32 v52, v52
	v_rcp_f32_e32 v53, v53
	v_rcp_f32_e32 v54, v54
	v_rcp_f32_e32 v55, v55
	v_rcp_f32_e32 v48, v48
	v_rcp_f32_e32 v49, v49
	v_rcp_f32_e32 v50, v50
	v_rcp_f32_e32 v51, v51
	v_add_u32_e32 v204, 0x80, v144
	v_ashrrev_i32_e32 v205, 31, v204
	v_lshlrev_b64 v[204:205], 12, v[204:205]
	v_lshl_add_u64 v[204:205], s[12:13], 0, v[204:205]
	v_lshl_add_u64 v[204:205], v[204:205], 0, v[146:147]
	v_mul_f32_e32 v52, v60, v52
	v_mul_f32_e32 v53, v61, v53
	v_mul_f32_e32 v54, v62, v54
	v_mul_f32_e32 v55, v63, v55
	v_mul_f32_e32 v48, v56, v48
	v_mul_f32_e32 v49, v57, v49
	v_mul_f32_e32 v50, v58, v50
	v_mul_f32_e32 v51, v59, v51
	v_rcp_f32_e32 v60, v60
	v_rcp_f32_e32 v61, v61
	v_rcp_f32_e32 v62, v62
	v_rcp_f32_e32 v63, v63
	v_rcp_f32_e32 v56, v56
	v_rcp_f32_e32 v57, v57
	v_rcp_f32_e32 v58, v58
	v_rcp_f32_e32 v59, v59
	v_cvt_pk_bf16_f32 v176, v52, v53
	v_cvt_pk_bf16_f32 v177, v54, v55
	v_cvt_pk_bf16_f32 v178, v48, v49
	v_cvt_pk_bf16_f32 v179, v50, v51
	v_cvt_pk_bf16_f32 v148, v60, v61
	v_cvt_pk_bf16_f32 v149, v62, v63
	v_cvt_pk_bf16_f32 v150, v56, v57
	v_cvt_pk_bf16_f32 v151, v58, v59
	global_store_dwordx4 v[204:205], v[148:151], off
; __device__ __forceinline__ u32x4 pack8(const float (&v)[8]) { u32x4 w; w.x = cvtpk(v[0], v[1]); w.y = cvtpk(v[2], v[3]); w.z = cvtpk(v[4], v[5]); w.w = cvtpk(v[6], v[7]); return w; }
;     __device__ __forceinline__ void operator()(const pg8::f32x4 (&acc)[2][2][4][2], const pg8::Unit& u, int wr, int wc, int fr, int fq) const {
;     ...
;                 const int c0 = (u.pn - 8) * 128 + wc * 32 + 8 * fq; float ba[8], bp[8];
; #pragma unroll
;                 for (int h = 0; h < 2; ++h) { const f32x4 a = *(const f32x4*)(rest.gate_b + c0 + 4 * h), p = *(const f32x4*)(rest.gate_b + 1024 + c0 + 4 * h);
; #pragma unroll
;                     for (int i = 0; i < 4; ++i) { ba[4 * h + i] = a[i]; bp[4 * h + i] = p[i]; } }
; #pragma unroll
;                 for (int ai = 0; ai < 2; ++ai)
; #pragma unroll
;                     for (int m = 0; m < 4; ++m) { ACC8(va, ai, 0, m); ACC8(vp, ai, 1, m); float oa[8], orr[8];
; #pragma unroll
;                         for (int i = 0; i < 8; ++i) { const float ea = fminf(1.0f + __builtin_amdgcn_exp2f(-LOG2E * (va[i] + ba[i])), 1e30f), ep = 1.0f + __builtin_amdgcn_exp2f(-LOG2E * (vp[i] + bp[i]));
;                             oa[i] = __builtin_amdgcn_rcpf(ea); orr[i] = ea * __builtin_amdgcn_rcpf(ep); }
;                         bf16_t* gp_ = rest.GATES + (size_t)(u.pm * 256 + ai * 128 + wr * 64 + m * 16 + fr) * 2048 + c0;
;                         *(u32x4*)gp_ = pack8(oa); *(u32x4*)(gp_ + 1024) = pack8(orr); }
	global_store_dwordx4 v[204:205], v[176:179], off offset:2048
	v_fmamk_f32 v44, v44, 0xbfb8aa3b, v140
	v_fmamk_f32 v45, v45, 0xbfb8aa3b, v141
	v_fmamk_f32 v46, v46, 0xbfb8aa3b, v142
	v_fmamk_f32 v47, v47, 0xbfb8aa3b, v143
	v_fmamk_f32 v40, v40, 0xbfb8aa3b, v132
	v_fmamk_f32 v41, v41, 0xbfb8aa3b, v133
	v_fmamk_f32 v42, v42, 0xbfb8aa3b, v134
	v_fmamk_f32 v43, v43, 0xbfb8aa3b, v135
	v_fmamk_f32 v36, v36, 0xbfb8aa3b, v136
	v_fmamk_f32 v37, v37, 0xbfb8aa3b, v137
	v_fmamk_f32 v38, v38, 0xbfb8aa3b, v138
	v_fmamk_f32 v39, v39, 0xbfb8aa3b, v139
	v_fmamk_f32 v32, v32, 0xbfb8aa3b, v128
	v_fmamk_f32 v33, v33, 0xbfb8aa3b, v129
	v_fmamk_f32 v34, v34, 0xbfb8aa3b, v130
	v_fmamk_f32 v35, v35, 0xbfb8aa3b, v131
	v_exp_f32_e32 v44, v44
	v_exp_f32_e32 v45, v45
	v_exp_f32_e32 v46, v46
	v_exp_f32_e32 v47, v47
	v_exp_f32_e32 v40, v40
	v_exp_f32_e32 v41, v41
	v_exp_f32_e32 v42, v42
	v_exp_f32_e32 v43, v43
	v_exp_f32_e32 v36, v36
	v_exp_f32_e32 v37, v37
	v_exp_f32_e32 v38, v38
	v_exp_f32_e32 v39, v39
	v_exp_f32_e32 v32, v32
	v_exp_f32_e32 v33, v33
	v_exp_f32_e32 v34, v34
	v_exp_f32_e32 v35, v35
	v_add_f32_e32 v44, 1.0, v44
	v_add_f32_e32 v45, 1.0, v45
	v_add_f32_e32 v46, 1.0, v46
	v_add_f32_e32 v47, 1.0, v47
	v_add_f32_e32 v40, 1.0, v40
	v_add_f32_e32 v41, 1.0, v41
	v_add_f32_e32 v42, 1.0, v42
	v_add_f32_e32 v43, 1.0, v43
	v_add_f32_e32 v36, 1.0, v36
	v_add_f32_e32 v37, 1.0, v37
	v_add_f32_e32 v38, 1.0, v38
	v_add_f32_e32 v39, 1.0, v39
	v_add_f32_e32 v32, 1.0, v32
	v_add_f32_e32 v33, 1.0, v33
	v_add_f32_e32 v34, 1.0, v34
	v_add_f32_e32 v35, 1.0, v35
	v_min_f32_e32 v44, 0x7149f2ca, v44
	v_min_f32_e32 v45, 0x7149f2ca, v45
	v_min_f32_e32 v46, 0x7149f2ca, v46
	v_min_f32_e32 v47, 0x7149f2ca, v47
	v_min_f32_e32 v40, 0x7149f2ca, v40
	v_min_f32_e32 v41, 0x7149f2ca, v41
	v_min_f32_e32 v42, 0x7149f2ca, v42
	v_min_f32_e32 v43, 0x7149f2ca, v43
	v_rcp_f32_e32 v36, v36
	v_rcp_f32_e32 v37, v37
	v_rcp_f32_e32 v38, v38
	v_rcp_f32_e32 v39, v39
	v_rcp_f32_e32 v32, v32
	v_rcp_f32_e32 v33, v33
	v_rcp_f32_e32 v34, v34
	v_rcp_f32_e32 v35, v35
	v_add_u32_e32 v206, 0x90, v144
	v_ashrrev_i32_e32 v207, 31, v206
	v_lshlrev_b64 v[206:207], 12, v[206:207]
	v_lshl_add_u64 v[206:207], s[12:13], 0, v[206:207]
	v_lshl_add_u64 v[206:207], v[206:207], 0, v[146:147]
	v_mul_f32_e32 v36, v44, v36
	v_mul_f32_e32 v37, v45, v37
	v_mul_f32_e32 v38, v46, v38
	v_mul_f32_e32 v39, v47, v39
	v_mul_f32_e32 v32, v40, v32
	v_mul_f32_e32 v33, v41, v33
	v_mul_f32_e32 v34, v42, v34
	v_mul_f32_e32 v35, v43, v35
	v_rcp_f32_e32 v44, v44
	v_rcp_f32_e32 v45, v45
	v_rcp_f32_e32 v46, v46
	v_rcp_f32_e32 v47, v47
	v_rcp_f32_e32 v40, v40
	v_rcp_f32_e32 v41, v41
	v_rcp_f32_e32 v42, v42
	v_rcp_f32_e32 v43, v43
	v_cvt_pk_bf16_f32 v176, v36, v37
	v_cvt_pk_bf16_f32 v177, v38, v39
	v_cvt_pk_bf16_f32 v178, v32, v33
	v_cvt_pk_bf16_f32 v179, v34, v35
	v_cvt_pk_bf16_f32 v148, v44, v45
	v_cvt_pk_bf16_f32 v149, v46, v47
	v_cvt_pk_bf16_f32 v150, v40, v41
	v_cvt_pk_bf16_f32 v151, v42, v43
	global_store_dwordx4 v[206:207], v[148:151], off
	global_store_dwordx4 v[206:207], v[176:179], off offset:2048
	v_fmamk_f32 v28, v28, 0xbfb8aa3b, v140
	v_fmamk_f32 v29, v29, 0xbfb8aa3b, v141
	v_fmamk_f32 v30, v30, 0xbfb8aa3b, v142
	v_fmamk_f32 v31, v31, 0xbfb8aa3b, v143
	v_fmamk_f32 v24, v24, 0xbfb8aa3b, v132
	v_fmamk_f32 v25, v25, 0xbfb8aa3b, v133
	v_fmamk_f32 v26, v26, 0xbfb8aa3b, v134
	v_fmamk_f32 v27, v27, 0xbfb8aa3b, v135
	v_fmamk_f32 v20, v20, 0xbfb8aa3b, v136
	v_fmamk_f32 v21, v21, 0xbfb8aa3b, v137
	v_fmamk_f32 v22, v22, 0xbfb8aa3b, v138
	v_fmamk_f32 v23, v23, 0xbfb8aa3b, v139
	v_fmamk_f32 v16, v16, 0xbfb8aa3b, v128
	v_fmamk_f32 v17, v17, 0xbfb8aa3b, v129
	v_fmamk_f32 v18, v18, 0xbfb8aa3b, v130
	v_fmamk_f32 v19, v19, 0xbfb8aa3b, v131
	v_exp_f32_e32 v28, v28
	v_exp_f32_e32 v29, v29
	v_exp_f32_e32 v30, v30
	v_exp_f32_e32 v31, v31
	v_exp_f32_e32 v24, v24
	v_exp_f32_e32 v25, v25
	v_exp_f32_e32 v26, v26
	v_exp_f32_e32 v27, v27
	v_exp_f32_e32 v20, v20
	v_exp_f32_e32 v21, v21
	v_exp_f32_e32 v22, v22
	v_exp_f32_e32 v23, v23
	v_exp_f32_e32 v16, v16
	v_exp_f32_e32 v17, v17
	v_exp_f32_e32 v18, v18
	v_exp_f32_e32 v19, v19
	v_add_f32_e32 v28, 1.0, v28
	v_add_f32_e32 v29, 1.0, v29
	v_add_f32_e32 v30, 1.0, v30
	v_add_f32_e32 v31, 1.0, v31
	v_add_f32_e32 v24, 1.0, v24
	v_add_f32_e32 v25, 1.0, v25
	v_add_f32_e32 v26, 1.0, v26
	v_add_f32_e32 v27, 1.0, v27
	v_add_f32_e32 v20, 1.0, v20
	v_add_f32_e32 v21, 1.0, v21
	v_add_f32_e32 v22, 1.0, v22
	v_add_f32_e32 v23, 1.0, v23
	v_add_f32_e32 v16, 1.0, v16
; __device__ __forceinline__ u32x4 pack8(const float (&v)[8]) { u32x4 w; w.x = cvtpk(v[0], v[1]); w.y = cvtpk(v[2], v[3]); w.z = cvtpk(v[4], v[5]); w.w = cvtpk(v[6], v[7]); return w; }
;     __device__ __forceinline__ void operator()(const pg8::f32x4 (&acc)[2][2][4][2], const pg8::Unit& u, int wr, int wc, int fr, int fq) const {
;     ...
;                 const int c0 = (u.pn - 8) * 128 + wc * 32 + 8 * fq; float ba[8], bp[8];
; #pragma unroll
;                 for (int h = 0; h < 2; ++h) { const f32x4 a = *(const f32x4*)(rest.gate_b + c0 + 4 * h), p = *(const f32x4*)(rest.gate_b + 1024 + c0 + 4 * h);
; #pragma unroll
;                     for (int i = 0; i < 4; ++i) { ba[4 * h + i] = a[i]; bp[4 * h + i] = p[i]; } }
; #pragma unroll
;                 for (int ai = 0; ai < 2; ++ai)
; #pragma unroll
;                     for (int m = 0; m < 4; ++m) { ACC8(va, ai, 0, m); ACC8(vp, ai, 1, m); float oa[8], orr[8];
; #pragma unroll
;                         for (int i = 0; i < 8; ++i) { const float ea = fminf(1.0f + __builtin_amdgcn_exp2f(-LOG2E * (va[i] + ba[i])), 1e30f), ep = 1.0f + __builtin_amdgcn_exp2f(-LOG2E * (vp[i] + bp[i]));
;                             oa[i] = __builtin_amdgcn_rcpf(ea); orr[i] = ea * __builtin_amdgcn_rcpf(ep); }
;                         bf16_t* gp_ = rest.GATES + (size_t)(u.pm * 256 + ai * 128 + wr * 64 + m * 16 + fr) * 2048 + c0;
;                         *(u32x4*)gp_ = pack8(oa); *(u32x4*)(gp_ + 1024) = pack8(orr); }
	v_add_f32_e32 v17, 1.0, v17
	v_add_f32_e32 v18, 1.0, v18
	v_add_f32_e32 v19, 1.0, v19
	v_min_f32_e32 v28, 0x7149f2ca, v28
	v_min_f32_e32 v29, 0x7149f2ca, v29
	v_min_f32_e32 v30, 0x7149f2ca, v30
	v_min_f32_e32 v31, 0x7149f2ca, v31
	v_min_f32_e32 v24, 0x7149f2ca, v24
	v_min_f32_e32 v25, 0x7149f2ca, v25
	v_min_f32_e32 v26, 0x7149f2ca, v26
	v_min_f32_e32 v27, 0x7149f2ca, v27
	v_rcp_f32_e32 v20, v20
	v_rcp_f32_e32 v21, v21
	v_rcp_f32_e32 v22, v22
	v_rcp_f32_e32 v23, v23
	v_rcp_f32_e32 v16, v16
	v_rcp_f32_e32 v17, v17
	v_rcp_f32_e32 v18, v18
	v_rcp_f32_e32 v19, v19
	v_add_u32_e32 v204, 0xa0, v144
	v_ashrrev_i32_e32 v205, 31, v204
	v_lshlrev_b64 v[204:205], 12, v[204:205]
	v_lshl_add_u64 v[204:205], s[12:13], 0, v[204:205]
	v_lshl_add_u64 v[204:205], v[204:205], 0, v[146:147]
	v_mul_f32_e32 v20, v28, v20
	v_mul_f32_e32 v21, v29, v21
	v_mul_f32_e32 v22, v30, v22
	v_mul_f32_e32 v23, v31, v23
	v_mul_f32_e32 v16, v24, v16
	v_mul_f32_e32 v17, v25, v17
	v_mul_f32_e32 v18, v26, v18
	v_mul_f32_e32 v19, v27, v19
	v_rcp_f32_e32 v28, v28
	v_rcp_f32_e32 v29, v29
	v_rcp_f32_e32 v30, v30
	v_rcp_f32_e32 v31, v31
	v_rcp_f32_e32 v24, v24
	v_rcp_f32_e32 v25, v25
	v_rcp_f32_e32 v26, v26
	v_rcp_f32_e32 v27, v27
	v_cvt_pk_bf16_f32 v176, v20, v21
	v_cvt_pk_bf16_f32 v177, v22, v23
	v_cvt_pk_bf16_f32 v178, v16, v17
	v_cvt_pk_bf16_f32 v179, v18, v19
	v_cvt_pk_bf16_f32 v148, v28, v29
	v_cvt_pk_bf16_f32 v149, v30, v31
	v_cvt_pk_bf16_f32 v150, v24, v25
	v_cvt_pk_bf16_f32 v151, v26, v27
	global_store_dwordx4 v[204:205], v[148:151], off
	global_store_dwordx4 v[204:205], v[176:179], off offset:2048
	v_fmamk_f32 v12, v12, 0xbfb8aa3b, v140
	v_fmamk_f32 v13, v13, 0xbfb8aa3b, v141
	v_fmamk_f32 v14, v14, 0xbfb8aa3b, v142
	v_fmamk_f32 v15, v15, 0xbfb8aa3b, v143
	v_fmamk_f32 v8, v8, 0xbfb8aa3b, v132
	v_fmamk_f32 v9, v9, 0xbfb8aa3b, v133
	v_fmamk_f32 v10, v10, 0xbfb8aa3b, v134
	v_fmamk_f32 v11, v11, 0xbfb8aa3b, v135
	v_fmamk_f32 v4, v4, 0xbfb8aa3b, v136
	v_fmamk_f32 v5, v5, 0xbfb8aa3b, v137
	v_fmamk_f32 v6, v6, 0xbfb8aa3b, v138
	v_fmamk_f32 v7, v7, 0xbfb8aa3b, v139
	v_fmamk_f32 v0, v0, 0xbfb8aa3b, v128
	v_fmamk_f32 v1, v1, 0xbfb8aa3b, v129
	v_fmamk_f32 v2, v2, 0xbfb8aa3b, v130
	v_fmamk_f32 v3, v3, 0xbfb8aa3b, v131
	v_exp_f32_e32 v12, v12
	v_exp_f32_e32 v13, v13
	v_exp_f32_e32 v14, v14
	v_exp_f32_e32 v15, v15
	v_exp_f32_e32 v8, v8
	v_exp_f32_e32 v9, v9
	v_exp_f32_e32 v10, v10
	v_exp_f32_e32 v11, v11
	v_exp_f32_e32 v4, v4
	v_exp_f32_e32 v5, v5
	v_exp_f32_e32 v6, v6
	v_exp_f32_e32 v7, v7
	v_exp_f32_e32 v0, v0
	v_exp_f32_e32 v1, v1
	v_exp_f32_e32 v2, v2
	v_exp_f32_e32 v3, v3
	v_add_f32_e32 v12, 1.0, v12
	v_add_f32_e32 v13, 1.0, v13
	v_add_f32_e32 v14, 1.0, v14
	v_add_f32_e32 v15, 1.0, v15
	v_add_f32_e32 v8, 1.0, v8
	v_add_f32_e32 v9, 1.0, v9
	v_add_f32_e32 v10, 1.0, v10
	v_add_f32_e32 v11, 1.0, v11
	v_add_f32_e32 v4, 1.0, v4
	v_add_f32_e32 v5, 1.0, v5
	v_add_f32_e32 v6, 1.0, v6
	v_add_f32_e32 v7, 1.0, v7
	v_add_f32_e32 v0, 1.0, v0
	v_add_f32_e32 v1, 1.0, v1
	v_add_f32_e32 v2, 1.0, v2
	v_add_f32_e32 v3, 1.0, v3
	v_min_f32_e32 v12, 0x7149f2ca, v12
	v_min_f32_e32 v13, 0x7149f2ca, v13
	v_min_f32_e32 v14, 0x7149f2ca, v14
	v_min_f32_e32 v15, 0x7149f2ca, v15
	v_min_f32_e32 v8, 0x7149f2ca, v8
	v_min_f32_e32 v9, 0x7149f2ca, v9
	v_min_f32_e32 v10, 0x7149f2ca, v10
	v_min_f32_e32 v11, 0x7149f2ca, v11
	v_rcp_f32_e32 v4, v4
	v_rcp_f32_e32 v5, v5
	v_rcp_f32_e32 v6, v6
	v_rcp_f32_e32 v7, v7
	v_rcp_f32_e32 v0, v0
	v_rcp_f32_e32 v1, v1
	v_rcp_f32_e32 v2, v2
	v_rcp_f32_e32 v3, v3
	v_add_u32_e32 v206, 0xb0, v144
	v_ashrrev_i32_e32 v207, 31, v206
	v_lshlrev_b64 v[206:207], 12, v[206:207]
	v_lshl_add_u64 v[206:207], s[12:13], 0, v[206:207]
	v_lshl_add_u64 v[206:207], v[206:207], 0, v[146:147]
	v_mul_f32_e32 v4, v12, v4
	v_mul_f32_e32 v5, v13, v5
	v_mul_f32_e32 v6, v14, v6
	v_mul_f32_e32 v7, v15, v7
	v_mul_f32_e32 v0, v8, v0
	v_mul_f32_e32 v1, v9, v1
	v_mul_f32_e32 v2, v10, v2
	v_mul_f32_e32 v3, v11, v3
	v_rcp_f32_e32 v12, v12
	v_rcp_f32_e32 v13, v13
	v_rcp_f32_e32 v14, v14
	v_rcp_f32_e32 v15, v15
	v_rcp_f32_e32 v8, v8
	v_rcp_f32_e32 v9, v9
	v_rcp_f32_e32 v10, v10
	v_rcp_f32_e32 v11, v11
	v_cvt_pk_bf16_f32 v176, v4, v5
	v_cvt_pk_bf16_f32 v177, v6, v7
	v_cvt_pk_bf16_f32 v178, v0, v1
	v_cvt_pk_bf16_f32 v179, v2, v3
	v_cvt_pk_bf16_f32 v148, v12, v13
	v_cvt_pk_bf16_f32 v149, v14, v15
	v_cvt_pk_bf16_f32 v150, v8, v9
	v_cvt_pk_bf16_f32 v151, v10, v11
	global_store_dwordx4 v[206:207], v[148:151], off
	global_store_dwordx4 v[206:207], v[176:179], off offset:2048
